# MoBA tile dispatch: hipcc's re-derived selection ballot (v_cndmask + v_cmp_ne) removed, s_cmp reads the v_cmp mask directly, both unrolled bodies
# speedup vs baseline: 1.0055x; 1.0055x over previous
; __device__ __forceinline__ void moba_unit(int b, int h, int j, const bf16_t* Q, const bf16_t* K, const bf16_t* VT, bf16_t* O, const float* biasd, const float* kmean, ALAS unsigned char* lds) {
;     ...
;         const bool sel = own ? true : (((selmask >> n) & 1u) != 0u);
;         const bool active = own ? (64 * t <= 32 * wid + 31) : (__any(sel) != 0);
;         if (active) {
.Lmb_540b:
	s_cmp_lg_u64 s[0:1], 0
	s_cselect_b64 s[8:9], -1, 0
	s_cbranch_execnz .Lmb_539b
